# v76 + F1 VALU diet: A-stage acc zero-fills only on skip paths, interleaved DPP scans with folded row_bcast, s_andn2 masks, 36 loop-invariant LDS address adds hoisted, off-diagonal tiles skip the trian
# speedup vs baseline: 1.0068x; 1.0068x over previous
.LBB0_865:
	s_andn2_b64 vcc, exec, s[8:9]
	s_cbranch_vccnz .LBB0_911
	v_writelane_b32 v254, s24, 44
	s_ashr_i32 s8, s18, 1
	s_lshl_b32 s12, s18, 3
	v_writelane_b32 v254, s25, 45
	s_and_b32 s20, s18, 3
	s_and_b32 s9, s8, -2
	s_lshl_b32 s17, s18, 5
	s_lshl_b32 s22, s18, 4
	v_writelane_b32 v254, s12, 46
	s_ashr_i32 s12, s12, 31
	v_writelane_b32 v254, s12, 47
	s_add_u32 s12, s36, 0x16600000
	s_addc_u32 s13, s37, 0
	v_writelane_b32 v254, s12, 48
	v_lshrrev_b32_e32 v2, 4, v114
	v_and_b32_e32 v28, 15, v1
	v_writelane_b32 v254, s13, 49
	s_add_u32 s12, s36, 0x32380000
	v_writelane_b32 v254, s12, 50
	s_addc_u32 s12, s37, 0
	v_writelane_b32 v254, s12, 51
	s_add_u32 s12, s36, 0x3a780000
	s_addc_u32 s13, s37, 0
	v_writelane_b32 v254, s12, 52
	v_lshlrev_b32_e32 v32, 2, v2
	v_lshlrev_b32_e32 v34, 3, v2
	v_writelane_b32 v254, s13, 53
	s_add_u32 s12, s36, 0x18700000
	s_addc_u32 s13, s37, 0
	v_writelane_b32 v254, s12, 54
	v_lshl_or_b32 v43, s8, 4, v28
	v_mul_lo_u32 v44, v43, s76
	v_writelane_b32 v254, s13, 55
	s_add_u32 s12, s36, 0x36580000
	v_writelane_b32 v254, s12, 56
	s_addc_u32 s12, s37, 0
	v_writelane_b32 v254, s12, 57
	s_add_u32 s12, s36, 0x29f80000
	v_writelane_b32 v254, s12, 58
	s_addc_u32 s12, s37, 0
	s_cmp_le_i32 s9, s20
	s_cselect_b64 s[28:29], -1, 0
	s_or_b32 s21, s8, 1
	v_writelane_b32 v254, s12, 59
	s_cmp_le_i32 s21, s20
	s_cselect_b64 s[24:25], -1, 0
	s_lshl_b32 s12, s20, 4
	s_lshl_b32 s19, s20, 5
	v_readlane_b32 s26, v254, 32
	v_or_b32_e32 v30, s12, v28
	v_or_b32_e32 v33, s12, v32
	s_add_i32 s12, s26, s19
	v_add_u32_e32 v119, s12, v34
	v_readlane_b32 s12, v254, 33
	v_readlane_b32 s34, v254, 37
	s_add_i32 s23, 0, 0x12000
	v_mov_b32_e32 v35, s12
	v_readlane_b32 s12, v254, 34
	s_waitcnt vmcnt(0)
	v_mad_u32_u24 v120, v30, s76, v35
	v_mul_u32_u24_e32 v31, 0x90, v30
	v_mov_b32_e32 v35, s12
	v_readlane_b32 s12, v254, 35
	v_mad_u32_u24 v122, v30, s76, v35
	v_readlane_b32 s27, v254, 36
	v_mov_b32_e32 v35, s12
	s_add_i32 s12, s34, s19
	v_add_u32_e32 v129, s12, v34
	s_and_b32 s12, s18, 2
	s_cmp_eq_u32 s9, s12
	s_cselect_b64 s[40:41], -1, 0
	s_cmp_lt_i32 s18, 2
	v_add3_u32 v118, s23, v31, v34
	v_add3_u32 v126, s27, v31, v34
	v_bfe_u32 v31, v1, 2, 2
	s_cselect_b64 s[42:43], -1, 0
	s_cmp_eq_u32 s18, 0
	v_mad_u32_u24 v124, v30, s76, v35
	v_or_b32_e32 v35, v34, v31
	s_cselect_b32 s12, 16, 48
	s_cselect_b32 s13, 0, 64
	v_or3_b32 v31, s17, v31, v34
	v_mul_lo_u32 v31, v31, s76
	s_add_i32 s16, s13, 0
	v_or_b32_e32 v39, s12, v28
	s_lshl_b32 s12, s18, 6
	v_add_u32_e32 v31, s16, v31
	s_add_i32 s16, s12, s23
	v_mov_b32_e32 v40, s16
	v_mad_u32_u24 v40, v39, s76, v40
	v_mad_u32_u24 v39, v39, s76, 0
	s_cmp_lt_i32 s18, 4
	v_add_u32_e32 v41, s13, v39
	v_add_u32_e32 v39, s12, v39
	s_cselect_b64 s[12:13], -1, 0
	s_and_b32 s16, s17, 32
	v_add_u32_e32 v44, 0x1200, v44
	v_mad_u32_u24 v35, v35, s76, 0
	v_add_u32_e32 v130, 0, v44
	s_cmp_gt_u32 s20, 1
	v_lshlrev_b32_e32 v36, 3, v1
	v_writelane_b32 v254, s17, 60
	v_add_u32_e32 v42, s16, v35
	v_add_u32_e32 v45, s23, v44
	v_add_u32_e32 v44, s16, v130
	s_cselect_b64 s[16:17], -1, 0
	s_add_i32 s8, s23, s19
	v_mad_u32_u24 v116, v30, s76, 0
	v_and_b32_e32 v36, 24, v36
	v_add_u32_e32 v132, s8, v34
	s_add_i32 s8, s27, s19
	v_and_b32_e32 v117, 48, v1
	v_add_u32_e32 v128, v35, v36
	v_or_b32_e32 v37, s19, v34
	v_add_u32_e32 v38, s19, v116
	v_add_u32_e32 v133, s8, v34
	v_add_u32_e32 v35, s19, v35
	v_readlane_b32 s19, v254, 38
	s_lshl_b32 s8, s20, 6
	v_lshlrev_b32_e32 v1, 1, v1
	s_add_i32 s8, s19, s8
	v_and_b32_e32 v46, 48, v114
	v_and_b32_e32 v1, 0x60, v1
	v_add_u32_e32 v135, s8, v46
	s_and_b32 s8, s18, 0xffffffc
	v_lshl_or_b32 v1, s20, 3, v1
	v_or_b32_e32 v46, s8, v2
	v_add_u32_e32 v136, s26, v1
	v_add_u32_e32 v137, 0, v1
	v_lshrrev_b32_e32 v1, 3, v0
	s_mov_b32 s8, 0xffffff0
	v_and_or_b32 v1, v1, s8, v28
	s_lshl_b32 s8, s9, 4
	s_lshl_b32 s30, s9, 5
	v_bfe_u32 v47, v0, 6, 1
	v_lshlrev_b32_e32 v104, 4, v0
	v_or_b32_e32 v0, s8, v28
	v_or_b32_e32 v48, 2, v33
	v_or_b32_e32 v49, 3, v33
	s_cmp_lg_u32 s9, s20
	v_lshl_add_u32 v134, v30, 2, s19
	v_mul_lo_u32 v140, v0, s76
	v_cmp_lt_i32_e64 s[44:45], v0, v33
	v_cmp_gt_i32_e64 s[46:47], v0, v33
	v_cmp_lt_i32_e64 s[18:19], v0, v48
	v_cmp_lt_i32_e64 s[62:63], v0, v49
	v_or_b32_e32 v0, s8, v32
	s_cselect_b64 s[64:65], -1, 0
	s_lshl_b32 s8, s21, 4
	v_or_b32_e32 v50, 1, v0
	v_cmp_eq_u32_e32 vcc, v0, v30
	v_or_b32_e32 v28, s8, v28
	v_cmp_lt_i32_e64 s[52:53], v50, v30
	v_cndmask_b32_e64 v106, 0, 1.0, vcc
	v_cmp_eq_u32_e32 vcc, v50, v30
	v_or_b32_e32 v50, 3, v0
	v_cmp_lt_i32_e64 s[70:71], v28, v48
	v_cndmask_b32_e64 v107, 0, 1.0, vcc
	v_or_b32_e32 v51, 2, v0
	v_cmp_eq_u32_e32 vcc, v50, v30
	v_writelane_b32 v254, s70, 61
	v_cmp_lt_i32_e64 s[66:67], v28, v33
	v_cndmask_b32_e64 v109, 0, 1.0, vcc
	v_cmp_eq_u32_e32 vcc, v51, v30
	v_cmp_gt_i32_e64 s[68:69], v28, v33
	v_writelane_b32 v254, s71, 62
	v_cmp_lt_i32_e64 s[70:71], v28, v49
	v_mul_lo_u32 v141, v28, s76
	v_or_b32_e32 v28, s8, v32
	v_cndmask_b32_e64 v108, 0, 1.0, vcc
	v_or_b32_e32 v32, 1, v28
	v_cmp_eq_u32_e32 vcc, v28, v30
	v_or_b32_e32 v43, 16, v43
	v_cmp_lt_i32_e64 s[74:75], v32, v30
	v_cndmask_b32_e64 v110, 0, 1.0, vcc
	v_cmp_eq_u32_e32 vcc, v32, v30
	v_or_b32_e32 v32, 3, v28
	v_lshlrev_b32_e32 v2, 5, v2
	v_mul_lo_u32 v1, v1, s76
	v_mul_lo_u32 v43, v43, s76
	v_writelane_b32 v254, s70, 63
	s_lshl_b32 s31, s21, 5
	v_cndmask_b32_e64 v111, 0, 1.0, vcc
	v_or_b32_e32 v33, 2, v28
	v_cmp_eq_u32_e32 vcc, v32, v30
	v_mad_u32_u24 v29, v114, s76, 0
	v_mad_u32_u24 v37, v30, s76, v37
	v_lshlrev_b32_e32 v46, 4, v46
	v_lshl_or_b32 v138, v47, 4, v2
	v_add_u32_e32 v139, 0, v1
	v_lshl_or_b32 v2, v47, 6, v117
	v_add_u32_e32 v1, s26, v1
	v_add_u32_e32 v47, 0, v140
	v_add_u32_e32 v43, 0, v43
	v_cmp_lt_i32_e64 s[48:49], v0, v30
	v_cmp_gt_i32_e64 s[50:51], v0, v30
	v_cmp_lt_i32_e64 s[54:55], v51, v30
	v_cmp_gt_i32_e64 s[56:57], v51, v30
	v_cmp_lt_i32_e64 s[58:59], v50, v30
	v_cmp_gt_i32_e64 s[60:61], v50, v30
	v_writelane_b32 v255, s71, 0
	v_cmp_lt_i32_e64 s[70:71], v28, v30
	v_cmp_gt_i32_e64 s[72:73], v28, v30
	v_cndmask_b32_e64 v113, 0, 1.0, vcc
	v_cmp_eq_u32_e32 vcc, v33, v30
	v_cmp_lt_i32_e64 s[76:77], v33, v30
	s_cmp_lg_u32 s21, s20
	v_cmp_gt_i32_e64 s[78:79], v33, v30
	v_add_u32_e32 v33, s23, v140
	v_add_u32_e32 v48, s23, v141
	v_add_u32_e32 v49, s34, v140
	v_add_u32_e32 v50, s34, v141
	v_add_u32_e32 v51, s27, v140
	v_lshlrev_b32_e32 v0, 1, v0
	v_add_u32_e32 v52, s27, v141
	v_lshlrev_b32_e32 v28, 1, v28
	v_cmp_ne_u32_e64 s[38:39], 63, v114
	v_xor_b32_e32 v115, 63, v114
	v_add_u32_e32 v121, v120, v34
	v_add_u32_e32 v123, v122, v34
	v_add_u32_e32 v125, v124, v34
	v_add_u32_e32 v127, v116, v34
	v_add_u32_e32 v131, s34, v117
	v_ashrrev_i32_e32 v105, 31, v104
	v_cndmask_b32_e64 v112, 0, 1.0, vcc
	s_cselect_b64 s[20:21], -1, 0
	v_add_u32_e32 v142, s22, v29
	s_lshl_b32 s26, s90, 6
	v_add_u32_e32 v143, v47, v117
	v_add_u32_e32 v144, v43, v117
	v_add_u32_e32 v145, 0, v37
	v_add_u32_e32 v146, v38, v34
	v_add_u32_e32 v147, v31, v36
	v_add_u32_e32 v148, v40, v117
	v_add_u32_e32 v149, v41, v34
	v_add_u32_e32 v150, v39, v117
	v_add_u32_e32 v151, v45, v117
	v_add_u32_e32 v152, v49, v117
	v_add_u32_e32 v153, v50, v117
	v_add_u32_e32 v154, v35, v36
	v_add_u32_e32 v155, v51, v117
	v_add_u32_e32 v156, v33, v117
	v_add_u32_e32 v157, v116, v0
	v_add_u32_e32 v158, v52, v117
	v_add_u32_e32 v159, v48, v117
	v_add_u32_e32 v160, v116, v28
	v_add_u32_e32 v161, v139, v2
	v_add_u32_e32 v162, v1, v138
	v_add_u32_e32 v163, v42, v36
	v_add_u32_e32 v164, v44, v34
	v_add_u32_e32 v165, v116, v46
	s_sub_i32 s27, 0x82, s90
	v_cmp_lt_i32_e64 s[80:81], v32, v30
	v_cmp_gt_i32_e64 s[82:83], v32, v30
	v_add_u32_e32 v166, v116, v117
	v_add_u32_e32 v167, s30, v118
	v_add_u32_e32 v168, v119, v140
	v_add_u32_e32 v169, s30, v121
	v_add_u32_e32 v170, s30, v123
	v_add_u32_e32 v171, s30, v126
	v_add_u32_e32 v172, s30, v125
	v_add_u32_e32 v173, s30, v127
	v_add_u32_e32 v174, s31, v118
	v_add_u32_e32 v175, v119, v141
	v_add_u32_e32 v176, s31, v121
	v_add_u32_e32 v177, s31, v123
	v_add_u32_e32 v178, s31, v126
	v_add_u32_e32 v179, s31, v125
	v_add_u32_e32 v182, s31, v127
	v_add_u32_e32 v183, v120, v117
	v_add_u32_e32 v184, s30, v128
	v_add_u32_e32 v185, s31, v128
	v_add_u32_e32 v186, v129, v140
	v_add_u32_e32 v187, v129, v141
	v_add_u32_e32 v188, 0x14400, v145
	v_add_u32_e32 v189, 0x16800, v145
	v_add_u32_e32 v190, v130, v117
	v_add_u32_e32 v191, v131, v140
	v_add_u32_e32 v192, v131, v141
	v_add_u32_e32 v193, v132, v140
	v_add_u32_e32 v194, v133, v140
	v_add_u32_e32 v195, v132, v141
	v_add_u32_e32 v196, v133, v141
	v_add_u32_e32 v197, v124, v117
	v_add_u32_e32 v200, v122, v117
	v_add_u32_e32 v201, v137, v140
	v_add_u32_e32 v204, v136, v141
	v_add_u32_e32 v205, 8, v165
	v_add_u32_e32 v206, v137, v141
	v_add_u32_e32 v207, v139, v138
.LBB0_867:
	s_waitcnt vmcnt(4)
	v_cvt_f32_f16 v44, v24
	v_lshrrev_b32_e32 v0, 16, v24
	v_cvt_f32_f16 v43, v0
	v_cvt_f32_f16 v38, v25
	v_lshrrev_b32_e32 v0, 16, v25
	v_cvt_f32_f16 v37, v0
	v_cvt_f32_f16 v36, v26
	v_lshrrev_b32_e32 v0, 16, v26
	v_cvt_f32_f16 v2, v0
	v_cvt_f32_f16 v1, v27
	v_lshrrev_b32_e32 v0, 16, v27
	v_cvt_f32_f16 v0, v0
	v_add_f32_dpp v32, v44, v44 row_shr:1 row_mask:0xf bank_mask:0xf bound_ctrl:1
	v_add_f32_dpp v47, v43, v43 row_shr:1 row_mask:0xf bank_mask:0xf bound_ctrl:1
	v_add_f32_dpp v45, v38, v38 row_shr:1 row_mask:0xf bank_mask:0xf bound_ctrl:1
	v_add_f32_dpp v46, v37, v37 row_shr:1 row_mask:0xf bank_mask:0xf bound_ctrl:1
	v_add_f32_dpp v41, v36, v36 row_shr:1 row_mask:0xf bank_mask:0xf bound_ctrl:1
	v_add_f32_dpp v42, v2, v2 row_shr:1 row_mask:0xf bank_mask:0xf bound_ctrl:1
	v_add_f32_dpp v39, v1, v1 row_shr:1 row_mask:0xf bank_mask:0xf bound_ctrl:1
	v_add_f32_dpp v40, v0, v0 row_shr:1 row_mask:0xf bank_mask:0xf bound_ctrl:1
	v_add_f32_dpp v32, v32, v32 row_shr:2 row_mask:0xf bank_mask:0xf bound_ctrl:1
	v_add_f32_dpp v47, v47, v47 row_shr:2 row_mask:0xf bank_mask:0xf bound_ctrl:1
	v_add_f32_dpp v45, v45, v45 row_shr:2 row_mask:0xf bank_mask:0xf bound_ctrl:1
	v_add_f32_dpp v46, v46, v46 row_shr:2 row_mask:0xf bank_mask:0xf bound_ctrl:1
	v_add_f32_dpp v41, v41, v41 row_shr:2 row_mask:0xf bank_mask:0xf bound_ctrl:1
	v_add_f32_dpp v42, v42, v42 row_shr:2 row_mask:0xf bank_mask:0xf bound_ctrl:1
	v_add_f32_dpp v39, v39, v39 row_shr:2 row_mask:0xf bank_mask:0xf bound_ctrl:1
	v_add_f32_dpp v40, v40, v40 row_shr:2 row_mask:0xf bank_mask:0xf bound_ctrl:1
	v_add_f32_dpp v32, v32, v32 row_shr:4 row_mask:0xf bank_mask:0xf bound_ctrl:1
	v_add_f32_dpp v47, v47, v47 row_shr:4 row_mask:0xf bank_mask:0xf bound_ctrl:1
	v_add_f32_dpp v45, v45, v45 row_shr:4 row_mask:0xf bank_mask:0xf bound_ctrl:1
	v_add_f32_dpp v46, v46, v46 row_shr:4 row_mask:0xf bank_mask:0xf bound_ctrl:1
	v_add_f32_dpp v41, v41, v41 row_shr:4 row_mask:0xf bank_mask:0xf bound_ctrl:1
	v_add_f32_dpp v42, v42, v42 row_shr:4 row_mask:0xf bank_mask:0xf bound_ctrl:1
	v_add_f32_dpp v39, v39, v39 row_shr:4 row_mask:0xf bank_mask:0xf bound_ctrl:1
	v_add_f32_dpp v40, v40, v40 row_shr:4 row_mask:0xf bank_mask:0xf bound_ctrl:1
	v_add_f32_dpp v32, v32, v32 row_shr:8 row_mask:0xf bank_mask:0xf bound_ctrl:1
	v_add_f32_dpp v47, v47, v47 row_shr:8 row_mask:0xf bank_mask:0xf bound_ctrl:1
	v_add_f32_dpp v45, v45, v45 row_shr:8 row_mask:0xf bank_mask:0xf bound_ctrl:1
	v_add_f32_dpp v46, v46, v46 row_shr:8 row_mask:0xf bank_mask:0xf bound_ctrl:1
	v_add_f32_dpp v41, v41, v41 row_shr:8 row_mask:0xf bank_mask:0xf bound_ctrl:1
	v_add_f32_dpp v42, v42, v42 row_shr:8 row_mask:0xf bank_mask:0xf bound_ctrl:1
	v_add_f32_dpp v39, v39, v39 row_shr:8 row_mask:0xf bank_mask:0xf bound_ctrl:1
	v_add_f32_dpp v40, v40, v40 row_shr:8 row_mask:0xf bank_mask:0xf bound_ctrl:1
	v_mov_b32_e32 v48, v3
	v_add_f32_dpp v32, v32, v32 row_bcast:15 row_mask:0xa bank_mask:0xf
	v_add_f32_dpp v47, v47, v47 row_bcast:15 row_mask:0xa bank_mask:0xf
	v_add_f32_dpp v45, v45, v45 row_bcast:15 row_mask:0xa bank_mask:0xf
	v_add_f32_dpp v46, v46, v46 row_bcast:15 row_mask:0xa bank_mask:0xf
	v_add_f32_dpp v41, v41, v41 row_bcast:15 row_mask:0xa bank_mask:0xf
	v_add_f32_dpp v42, v42, v42 row_bcast:15 row_mask:0xa bank_mask:0xf
	v_add_f32_dpp v39, v39, v39 row_bcast:15 row_mask:0xa bank_mask:0xf
	v_add_f32_dpp v40, v40, v40 row_bcast:15 row_mask:0xa bank_mask:0xf
	v_mov_b32_dpp v48, v32 row_bcast:31 row_mask:0xc bank_mask:0xf
	v_add_f32_dpp v47, v47, v47 row_bcast:31 row_mask:0xc bank_mask:0xf
	v_add_f32_dpp v45, v45, v45 row_bcast:31 row_mask:0xc bank_mask:0xf
	v_add_f32_dpp v46, v46, v46 row_bcast:31 row_mask:0xc bank_mask:0xf
	v_add_f32_dpp v41, v41, v41 row_bcast:31 row_mask:0xc bank_mask:0xf
	v_add_f32_dpp v42, v42, v42 row_bcast:31 row_mask:0xc bank_mask:0xf
	v_add_f32_dpp v39, v39, v39 row_bcast:31 row_mask:0xc bank_mask:0xf
	v_add_f32_dpp v40, v40, v40 row_bcast:31 row_mask:0xc bank_mask:0xf
	v_mul_f32_e32 v49, 0x3fb8aa3b, v47
	v_mul_f32_e32 v30, 0x3fb8aa3b, v41
	v_mul_f32_e32 v31, 0x3fb8aa3b, v42
	v_mul_f32_e32 v50, 0x3fb8aa3b, v39
	v_mul_f32_e32 v28, 0x3fb8aa3b, v45
	v_mul_f32_e32 v29, 0x3fb8aa3b, v46
	v_mul_f32_e32 v51, 0x3fb8aa3b, v40
	v_exp_f32_e32 v33, v49
	v_exp_f32_e32 v34, v28
	v_exp_f32_e32 v35, v29
	v_exp_f32_e32 v28, v30
	v_exp_f32_e32 v29, v31
	v_exp_f32_e32 v30, v50
	v_exp_f32_e32 v31, v51
	s_and_saveexec_b64 s[8:9], s[38:39]
	s_xor_b64 s[22:23], exec, s[8:9]
	v_exp_f32_e32 v33, v49
	s_or_saveexec_b64 s[22:23], s[22:23]
	v_add_f32_e32 v48, v32, v48
	v_mul_f32_e32 v32, 0x3fb8aa3b, v48
	v_exp_f32_e32 v32, v32
	s_xor_b64 exec, exec, s[22:23]
	s_cbranch_execz .LBB0_871
	v_readlane_b32 s8, v254, 60
	s_add_i32 s8, s8, 0
	s_add_i32 s8, s8, 0x21c00
	v_mov_b32_e32 v49, s8
	ds_write_b128 v49, v[32:35]
	ds_write_b128 v49, v[28:31] offset:16

.LBB0_877:
	s_waitcnt lgkmcnt(0)
	s_barrier
	s_andn2_b64 s[84:85], exec, s[28:29]
	s_andn2_b64 vcc, exec, s[28:29]
	s_cbranch_vccnz .LBB0_881
	ds_read_b128 v[36:39], v166
	ds_read_b128 v[40:43], v166 offset:64
	ds_read_b128 v[28:31], v166 offset:27648
	ds_read_b128 v[32:35], v166 offset:27712
	s_and_b64 vcc, exec, s[84:85]
	s_cbranch_vccz .LBB0_882
.LBB0_879:
	v_mov_b32_e32 v80, 0
	v_mov_b32_e32 v81, 0
	v_mov_b32_e32 v82, 0
	v_mov_b32_e32 v83, 0
	v_mov_b32_e32 v88, 0
	v_mov_b32_e32 v89, 0
	v_mov_b32_e32 v90, 0
	v_mov_b32_e32 v91, 0
	v_mov_b32_e32 v92, 0
	v_mov_b32_e32 v93, 0
	v_mov_b32_e32 v94, 0
	v_mov_b32_e32 v95, 0
	v_mov_b32_e32 v96, 0
	v_mov_b32_e32 v97, 0
	v_mov_b32_e32 v98, 0
	v_mov_b32_e32 v99, 0
	s_andn2_b64 s[86:87], exec, s[24:25]
	s_andn2_b64 vcc, exec, s[24:25]
	s_cbranch_vccz .LBB0_883

.LBB0_882:
	ds_read_b128 v[92:95], v143 offset:9216
	ds_read_b128 v[96:99], v143 offset:9280
	ds_read_b128 v[80:83], v143 offset:18432
	ds_read_b128 v[88:91], v143 offset:18496
	s_andn2_b64 s[86:87], exec, s[24:25]
	s_andn2_b64 vcc, exec, s[24:25]
	s_cbranch_vccnz .LBB0_880

.LBB0_884:
	s_and_b64 vcc, exec, s[84:85]
	s_cbranch_vccz .Lf1_mm1
	v_mov_b32_e32 v64, 0
	v_mov_b32_e32 v65, 0
	v_mov_b32_e32 v66, 0
	v_mov_b32_e32 v67, 0
	v_mov_b32_e32 v68, 0
	v_mov_b32_e32 v69, 0
	v_mov_b32_e32 v70, 0
	v_mov_b32_e32 v71, 0
	v_mov_b32_e32 v76, 0
	v_mov_b32_e32 v77, 0
	v_mov_b32_e32 v78, 0
	v_mov_b32_e32 v79, 0
	v_mov_b32_e32 v72, 0
	v_mov_b32_e32 v73, 0
	v_mov_b32_e32 v74, 0
	v_mov_b32_e32 v75, 0
	v_mov_b32_e32 v84, 0
	v_mov_b32_e32 v85, 0
	v_mov_b32_e32 v86, 0
	v_mov_b32_e32 v87, 0
	s_branch .LBB0_886
.Lf1_mm1:
	s_waitcnt lgkmcnt(3)
	v_mfma_f32_16x16x32_bf16 v[64:67], v[92:95], v[36:39], 0
	s_waitcnt lgkmcnt(2)
	v_mfma_f32_16x16x32_bf16 v[84:87], v[96:99], v[40:43], v[64:67]
	v_mfma_f32_16x16x32_bf16 v[64:67], v[36:39], v[92:95], 0
	v_mfma_f32_16x16x32_bf16 v[72:75], v[40:43], v[96:99], v[64:67]
	s_waitcnt lgkmcnt(1)
	v_mfma_f32_16x16x32_bf16 v[64:67], v[80:83], v[36:39], 0
	s_waitcnt lgkmcnt(0)
	v_mfma_f32_16x16x32_bf16 v[76:79], v[88:91], v[40:43], v[64:67]
	v_mfma_f32_16x16x32_bf16 v[64:67], v[92:95], v[28:31], 0
	v_mfma_f32_16x16x32_bf16 v[68:71], v[96:99], v[32:35], v[64:67]
	v_mfma_f32_16x16x32_bf16 v[64:67], v[80:83], v[28:31], 0
	v_mfma_f32_16x16x32_bf16 v[64:67], v[88:91], v[32:35], v[64:67]
.LBB0_886:
	s_and_b64 vcc, exec, s[86:87]
	s_waitcnt lgkmcnt(0)
	s_cbranch_vccz .Lf1_mm2
	v_mov_b32_e32 v44, 0
	v_mov_b32_e32 v45, 0
	v_mov_b32_e32 v46, 0
	v_mov_b32_e32 v47, 0
	v_mov_b32_e32 v88, 0
	v_mov_b32_e32 v89, 0
	v_mov_b32_e32 v90, 0
	v_mov_b32_e32 v91, 0
	v_mov_b32_e32 v92, 0
	v_mov_b32_e32 v93, 0
	v_mov_b32_e32 v94, 0
	v_mov_b32_e32 v95, 0
	v_mov_b32_e32 v80, 0
	v_mov_b32_e32 v81, 0
	v_mov_b32_e32 v82, 0
	v_mov_b32_e32 v83, 0
	v_mov_b32_e32 v96, 0
	v_mov_b32_e32 v97, 0
	v_mov_b32_e32 v98, 0
	v_mov_b32_e32 v99, 0
	s_branch .LBB0_888
.Lf1_mm2:
	v_mfma_f32_16x16x32_bf16 v[44:47], v[56:59], v[36:39], 0
	v_mfma_f32_16x16x32_bf16 v[96:99], v[60:63], v[40:43], v[44:47]
	v_mfma_f32_16x16x32_bf16 v[44:47], v[36:39], v[56:59], 0
	v_mfma_f32_16x16x32_bf16 v[36:39], v[48:51], v[36:39], 0
	v_mfma_f32_16x16x32_bf16 v[92:95], v[52:55], v[40:43], v[36:39]
	v_mfma_f32_16x16x32_bf16 v[36:39], v[56:59], v[28:31], 0
	v_mfma_f32_16x16x32_bf16 v[28:31], v[48:51], v[28:31], 0
	v_mfma_f32_16x16x32_bf16 v[80:83], v[40:43], v[60:63], v[44:47]
	v_mfma_f32_16x16x32_bf16 v[88:91], v[60:63], v[32:35], v[36:39]
	v_mfma_f32_16x16x32_bf16 v[44:47], v[52:55], v[32:35], v[28:31]
.LBB0_888:
	s_mov_b64 s[86:87], 0x10000
	s_and_b64 vcc, exec, s[64:65]
	s_cbranch_vccz .Lf1_q0_diag
	v_cvt_pk_bf16_f32 v30, v84, v85
	v_cvt_pk_bf16_f32 v31, v86, v87
	ds_write_b64 v167, v[30:31]
	ds_write_b64 v171, v[30:31]
	v_cvt_pk_bf16_f32 v28, v72, v73
	v_cvt_pk_bf16_f32 v29, v74, v75
	ds_write_b64 v168, v[28:29]
	v_cvt_pk_bf16_f32 v32, v76, v77
	v_cvt_pk_bf16_f32 v33, v78, v79
	ds_write_b64 v169, v[32:33]
	v_cvt_pk_bf16_f32 v34, v68, v69
	v_cvt_pk_bf16_f32 v35, v70, v71
	ds_write_b64 v170, v[34:35]
	v_cvt_pk_bf16_f32 v36, v64, v65
	v_cvt_pk_bf16_f32 v37, v66, v67
	ds_write_b64 v172, v[36:37]
	ds_write_b64 v173, v[210:211] offset:46080
	ds_write_b64 v173, v[210:211] offset:64512
	s_branch .LBB0_890
.Lf1_q0_diag:
	v_cndmask_b32_e64 v0, v68, 0, s[50:51]
	s_or_b64 vcc, s[58:59], s[54:55]
	s_nop 1
	v_cndmask_b32_e64 v36, v0, v68, s[48:49]
	v_cndmask_b32_e32 v0, 0, v86, vcc
	s_or_b64 vcc, vcc, s[52:53]
	v_cndmask_b32_e32 v29, 0, v85, vcc
	s_or_b64 vcc, vcc, s[48:49]
	v_cndmask_b32_e64 v1, 0, v87, s[58:59]
	v_cndmask_b32_e32 v28, 0, v84, vcc
	v_cndmask_b32_e64 v33, 0, v72, s[44:45]
	v_cndmask_b32_e64 v38, v73, 0, s[46:47]
	v_cndmask_b32_e64 v42, 0, v74, s[18:19]
	v_cndmask_b32_e64 v50, 0, v75, s[62:63]
	v_cvt_pk_bf16_f32 v30, v28, v29
	v_cvt_pk_bf16_f32 v31, v0, v1
	v_cndmask_b32_e64 v2, 0, v76, s[48:49]
	v_cndmask_b32_e64 v34, 0, v77, s[52:53]
	v_cndmask_b32_e64 v39, 0, v78, s[54:55]
	v_cndmask_b32_e64 v43, 0, v79, s[58:59]
	ds_write_b64 v167, v[30:31]
	v_cvt_pk_bf16_f32 v30, v33, v38
	v_cvt_pk_bf16_f32 v31, v42, v50
	v_cndmask_b32_e64 v35, 0, v69, s[48:49]
	v_cndmask_b32_e64 v40, v70, 0, s[56:57]
	v_cndmask_b32_e64 v48, v71, 0, s[60:61]
	ds_write_b64 v168, v[30:31]
	v_cvt_pk_bf16_f32 v30, v2, v34
	v_cvt_pk_bf16_f32 v31, v39, v43
	v_pk_add_f32 v[28:29], v[106:107], v[28:29]
	v_pk_add_f32 v[0:1], v[108:109], v[0:1]
	v_cndmask_b32_e64 v32, v64, 0, s[50:51]
	v_cndmask_b32_e64 v37, 0, v65, s[48:49]
	v_cndmask_b32_e64 v41, v66, 0, s[56:57]
	v_cndmask_b32_e64 v49, v67, 0, s[60:61]
	ds_write_b64 v169, v[30:31]
	v_cvt_pk_bf16_f32 v30, v36, v35
	v_cvt_pk_bf16_f32 v31, v40, v48
	v_cvt_pk_bf16_f32 v28, v28, v29
	v_cvt_pk_bf16_f32 v29, v0, v1
	ds_write_b64 v170, v[30:31]
	v_cvt_pk_bf16_f32 v30, v32, v37
	v_cvt_pk_bf16_f32 v31, v41, v49
	ds_write_b64 v171, v[28:29]
	s_andn2_b64 vcc, exec, s[64:65]
	s_mov_b64 s[86:87], 0x10000
	ds_write_b64 v172, v[30:31]
	ds_write_b64 v173, v[210:211] offset:46080
	s_cbranch_vccnz .LBB0_890
	ds_write_b64 v173, v[210:211] offset:64512
.LBB0_890:
	s_and_b64 vcc, exec, s[20:21]
	s_cbranch_vccz .Lf1_q1_diag
	v_cvt_pk_bf16_f32 v30, v96, v97
	v_cvt_pk_bf16_f32 v31, v98, v99
	ds_write_b64 v174, v[30:31]
	ds_write_b64 v178, v[30:31]
	v_cvt_pk_bf16_f32 v28, v80, v81
	v_cvt_pk_bf16_f32 v29, v82, v83
	ds_write_b64 v175, v[28:29]
	v_cvt_pk_bf16_f32 v32, v92, v93
	v_cvt_pk_bf16_f32 v33, v94, v95
	ds_write_b64 v176, v[32:33]
	v_cvt_pk_bf16_f32 v34, v88, v89
	v_cvt_pk_bf16_f32 v35, v90, v91
	ds_write_b64 v177, v[34:35]
	v_cvt_pk_bf16_f32 v36, v44, v45
	v_cvt_pk_bf16_f32 v37, v46, v47
	ds_write_b64 v179, v[36:37]
	ds_write_b64 v182, v[210:211] offset:46080
	ds_write_b64 v182, v[210:211] offset:64512
	s_branch .LBB0_892
.Lf1_q1_diag:
	v_cndmask_b32_e64 v0, v88, 0, s[72:73]
	v_readlane_b32 s8, v254, 61
	s_or_b64 vcc, s[80:81], s[76:77]
	v_cndmask_b32_e64 v36, v0, v88, s[70:71]
	v_readlane_b32 s9, v254, 62
	v_cndmask_b32_e32 v0, 0, v98, vcc
	s_or_b64 vcc, vcc, s[74:75]
	v_cndmask_b32_e64 v42, 0, v82, s[8:9]
	v_cndmask_b32_e32 v29, 0, v97, vcc
	s_or_b64 vcc, vcc, s[70:71]
	v_readlane_b32 s8, v254, 63
	v_cndmask_b32_e64 v1, 0, v99, s[80:81]
	v_cndmask_b32_e32 v28, 0, v96, vcc
	v_readlane_b32 s9, v255, 0
	v_cndmask_b32_e64 v33, 0, v80, s[66:67]
	v_cndmask_b32_e64 v37, 0, v45, s[70:71]
	v_cndmask_b32_e64 v38, v81, 0, s[68:69]
	v_cndmask_b32_e64 v41, v46, 0, s[78:79]
	v_cndmask_b32_e64 v45, v47, 0, s[82:83]
	v_cndmask_b32_e64 v46, 0, v83, s[8:9]
	v_cvt_pk_bf16_f32 v30, v28, v29
	v_cvt_pk_bf16_f32 v31, v0, v1
	v_cndmask_b32_e64 v2, 0, v92, s[70:71]
	v_cndmask_b32_e64 v34, 0, v93, s[74:75]
	v_cndmask_b32_e64 v39, 0, v94, s[76:77]
	v_cndmask_b32_e64 v43, 0, v95, s[80:81]
	ds_write_b64 v174, v[30:31]
	v_cvt_pk_bf16_f32 v30, v33, v38
	v_cvt_pk_bf16_f32 v31, v42, v46
	v_cndmask_b32_e64 v32, v44, 0, s[72:73]
	v_cndmask_b32_e64 v35, 0, v89, s[70:71]
	v_cndmask_b32_e64 v40, v90, 0, s[78:79]
	v_cndmask_b32_e64 v44, v91, 0, s[82:83]
	ds_write_b64 v175, v[30:31]
	v_cvt_pk_bf16_f32 v30, v2, v34
	v_cvt_pk_bf16_f32 v31, v39, v43
	v_pk_add_f32 v[28:29], v[110:111], v[28:29]
	v_pk_add_f32 v[0:1], v[112:113], v[0:1]
	ds_write_b64 v176, v[30:31]
	v_cvt_pk_bf16_f32 v30, v36, v35
	v_cvt_pk_bf16_f32 v31, v40, v44
	v_cvt_pk_bf16_f32 v28, v28, v29
	v_cvt_pk_bf16_f32 v29, v0, v1
	ds_write_b64 v177, v[30:31]
	v_cvt_pk_bf16_f32 v30, v32, v37
	v_cvt_pk_bf16_f32 v31, v41, v45
	ds_write_b64 v178, v[28:29]
	s_andn2_b64 vcc, exec, s[20:21]
	ds_write_b64 v179, v[30:31]
	ds_write_b64 v182, v[210:211] offset:46080
	s_cbranch_vccnz .LBB0_892
	ds_write_b64 v182, v[210:211] offset:64512
.LBB0_892:
	s_waitcnt lgkmcnt(0)
	s_barrier
	ds_read_b128 v[44:47], v183
	ds_read_b128 v[48:51], v183 offset:64
	ds_read_b64_tr_b16 v[40:41], v184 offset:36864
	ds_read_b64_tr_b16 v[42:43], v184 offset:37440
	ds_read_b64_tr_b16 v[36:37], v184 offset:41472
	ds_read_b64_tr_b16 v[38:39], v184 offset:42048
	s_waitcnt lgkmcnt(2)
	v_mfma_f32_16x16x32_bf16 v[28:31], v[44:47], v[40:43], 0
	s_andn2_b64 vcc, exec, s[40:41]
	s_waitcnt lgkmcnt(0)
	v_mfma_f32_16x16x32_bf16 v[52:55], v[48:51], v[36:39], v[28:31]
	ds_read_b64_tr_b16 v[32:33], v185 offset:36864
	ds_read_b64_tr_b16 v[34:35], v185 offset:37440
	s_nop 0
	ds_read_b64_tr_b16 v[28:29], v185 offset:41472
	ds_read_b64_tr_b16 v[30:31], v185 offset:42048
	s_nop 2
	v_cvt_pk_bf16_f32 v0, v52, v53
	s_waitcnt lgkmcnt(2)
	v_mfma_f32_16x16x32_bf16 v[44:47], v[44:47], v[32:35], 0
	v_cvt_pk_bf16_f32 v1, v54, v55
	ds_write_b64 v186, v[0:1]
	s_nop 0
	s_waitcnt lgkmcnt(1)
	v_mfma_f32_16x16x32_bf16 v[44:47], v[48:51], v[28:31], v[44:47]
	s_nop 7
	v_cvt_pk_bf16_f32 v0, v44, v45
	v_cvt_pk_bf16_f32 v1, v46, v47
	ds_write_b64 v187, v[0:1]
	s_cbranch_vccnz .LBB0_894
	v_add_u32_e32 v0, 0x12000, v145
	ds_read_b64 v[0:1], v0
	ds_read_b64 v[44:45], v188
	ds_read_b64 v[48:49], v189
	v_mov_b32_e32 v2, v3
	v_mov_b32_e32 v46, v3
	v_mov_b32_e32 v47, v3
	v_mov_b32_e32 v64, v3
	v_mov_b32_e32 v65, v3
	s_waitcnt lgkmcnt(1)
	v_mfma_f32_16x16x32_bf16 v[54:57], v[0:3], v[44:47], 0
	v_mov_b32_e32 v50, v3
	v_mov_b32_e32 v51, v3
	s_waitcnt lgkmcnt(0)
	v_lshlrev_b32_e32 v52, 16, v48
	v_mfma_f32_16x16x32_bf16 v[44:47], v[44:47], v[0:3], 0
	v_and_b32_e32 v53, 0xffff0000, v48
	s_nop 1
	v_cvt_pk_bf16_f32 v62, v54, v55
	v_cvt_pk_bf16_f32 v63, v56, v57
	v_lshlrev_b32_e32 v54, 16, v49
	v_and_b32_e32 v55, 0xffff0000, v49
	s_nop 0
	v_cvt_pk_bf16_f32 v0, v44, v45
	v_cvt_pk_bf16_f32 v1, v46, v47
	v_mfma_f32_16x16x32_bf16 v[48:51], v[62:65], v[48:51], v[52:55]
	s_nop 0
	v_mfma_f32_16x16x32_bf16 v[44:47], v[62:65], v[0:3], 0
	v_mfma_f32_16x16x32_bf16 v[52:55], v[0:3], v[62:65], 0
	s_nop 6
	v_cvt_pk_bf16_f32 v0, v44, v45
	v_cvt_pk_bf16_f32 v1, v46, v47
	v_cvt_pk_bf16_f32 v44, v52, v53
	v_cvt_pk_bf16_f32 v45, v54, v55
	v_mov_b32_e32 v46, v3
	v_mov_b32_e32 v47, v3
	v_cvt_pk_bf16_f32 v52, v48, v49
	v_cvt_pk_bf16_f32 v53, v50, v51
	v_mov_b32_e32 v54, v3
	v_mov_b32_e32 v55, v3
	s_nop 1
	v_mfma_f32_16x16x32_bf16 v[48:51], v[44:47], v[52:55], v[48:51]
	v_mfma_f32_16x16x32_bf16 v[44:47], v[0:3], v[44:47], 0
	s_nop 7
	v_cvt_pk_bf16_f32 v0, v44, v45
	v_cvt_pk_bf16_f32 v1, v46, v47
	v_cvt_pk_bf16_f32 v44, v48, v49
	v_cvt_pk_bf16_f32 v45, v50, v51
	v_mov_b32_e32 v46, v3
	v_mov_b32_e32 v47, v3
	s_nop 1
	v_mfma_f32_16x16x32_bf16 v[44:47], v[0:3], v[44:47], v[48:51]
	s_nop 7
	v_cvt_pk_bf16_f32 v0, v44, v45
	v_cvt_pk_bf16_f32 v1, v46, v47
	ds_write_b64 v146, v[0:1] offset:64512

.LBB0_896:
	s_waitcnt lgkmcnt(0)
	s_barrier
	s_andn2_b64 s[84:85], exec, s[12:13]
	s_andn2_b64 vcc, exec, s[12:13]
	s_cbranch_vccnz .LBB0_898
	ds_read_b64_tr_b16 v[46:47], v163 offset:65088
	ds_read_b64_tr_b16 v[44:45], v163 offset:64512
	ds_read_b128 v[48:51], v151
	s_waitcnt lgkmcnt(0)
	v_mfma_f32_16x16x32_bf16 v[44:47], v[44:47], v[48:51], 0
	s_nop 7
	v_cvt_pk_bf16_f32 v0, v44, v45
	v_cvt_pk_bf16_f32 v1, v46, v47
	ds_write_b64 v164, v[0:1] offset:46080
.LBB0_898:
	s_waitcnt lgkmcnt(0)
	s_barrier
	s_and_b64 vcc, exec, s[84:85]
	s_cbranch_vccnz .LBB0_900
	ds_read_b64_tr_b16 v[44:45], v163 offset:50688
	ds_read_b64_tr_b16 v[46:47], v163 offset:51264
	ds_read_b128 v[48:51], v190 offset:64576
	s_waitcnt lgkmcnt(0)
	v_mfma_f32_16x16x32_bf16 v[44:47], v[44:47], v[48:51], 0
	s_nop 7
	v_cvt_pk_bf16_f32 v0, v44, v45
	v_cvt_pk_bf16_f32 v1, v46, v47
	ds_write_b64 v164, v[0:1] offset:64512
.LBB0_900:
	s_waitcnt lgkmcnt(0)
	s_barrier
	ds_read_b128 v[48:51], v166 offset:64512
	ds_read_b64_tr_b16 v[44:45], v184
	ds_read_b64_tr_b16 v[46:47], v184 offset:576
	ds_read_b64_tr_b16 v[52:53], v185
	ds_read_b64_tr_b16 v[54:55], v185 offset:576
	ds_read_b128 v[56:59], v191
	ds_read_b128 v[62:65], v192
	s_waitcnt lgkmcnt(4)
	v_mfma_f32_16x16x32_bf16 v[44:47], v[48:51], v[44:47], 0
	s_andn2_b64 s[84:85], exec, s[16:17]
	s_andn2_b64 vcc, exec, s[16:17]
	s_waitcnt lgkmcnt(1)
	v_mfma_f32_16x16x32_bf16 v[56:59], v[48:51], v[56:59], 0
	v_mfma_f32_16x16x32_bf16 v[52:55], v[48:51], v[52:55], 0
	s_waitcnt lgkmcnt(0)
	v_mfma_f32_16x16x32_bf16 v[48:51], v[48:51], v[62:65], 0
	s_cbranch_vccnz .LBB0_902
	ds_read_b128 v[62:65], v166 offset:64576
	ds_read_b64_tr_b16 v[66:67], v184 offset:4608
	ds_read_b64_tr_b16 v[68:69], v184 offset:5184
	s_waitcnt lgkmcnt(0)
	v_mfma_f32_16x16x32_bf16 v[44:47], v[62:65], v[66:69], v[44:47]
	ds_read_b128 v[66:69], v152 offset:64
	s_waitcnt lgkmcnt(0)
	v_mfma_f32_16x16x32_bf16 v[56:59], v[62:65], v[66:69], v[56:59]
	ds_read_b64_tr_b16 v[66:67], v185 offset:4608
	ds_read_b64_tr_b16 v[68:69], v185 offset:5184
	s_waitcnt lgkmcnt(0)
	v_mfma_f32_16x16x32_bf16 v[52:55], v[62:65], v[66:69], v[52:55]
	ds_read_b128 v[66:69], v153 offset:64
	s_waitcnt lgkmcnt(0)
	v_mfma_f32_16x16x32_bf16 v[48:51], v[62:65], v[66:69], v[48:51]
.LBB0_902:
	v_cvt_pk_bf16_f32 v0, v44, v45
	v_cvt_pk_bf16_f32 v1, v46, v47
	s_nop 0
	ds_write_b64 v193, v[0:1]
	v_cvt_pk_bf16_f32 v0, v56, v57
	v_cvt_pk_bf16_f32 v1, v58, v59
	s_nop 0
	ds_write_b64 v194, v[0:1]
	v_cvt_pk_bf16_f32 v0, v52, v53
	v_cvt_pk_bf16_f32 v1, v54, v55
	s_nop 0
	ds_write_b64 v195, v[0:1]
	v_cvt_pk_bf16_f32 v0, v48, v49
	v_cvt_pk_bf16_f32 v1, v50, v51
	ds_write_b64 v196, v[0:1]
	s_waitcnt lgkmcnt(0)
	s_barrier
	ds_read_b128 v[76:79], v197
	ds_read_b128 v[72:75], v200
	s_and_b64 vcc, exec, s[84:85]
	s_waitcnt lgkmcnt(1)
	v_mov_b64_e32 v[68:69], v[76:77]
	s_waitcnt lgkmcnt(0)
	v_mov_b64_e32 v[64:65], v[72:73]
	v_mov_b64_e32 v[70:71], v[78:79]
	v_mov_b64_e32 v[66:67], v[74:75]
	s_cbranch_vccnz .LBB0_904
	ds_read_b128 v[64:67], v200 offset:64
	ds_read_b128 v[68:71], v197 offset:64

.LBB0_906:
	v_mfma_f32_16x16x32_bf16 v[80:83], v[60:63], v[80:83], 0
	v_add_u32_e32 v1, v136, v140
	s_and_b64 vcc, exec, s[84:85]
	v_mfma_f32_16x16x32_bf16 v[80:83], v[56:59], v[84:87], v[80:83]
	v_mfma_f32_16x16x32_bf16 v[88:91], v[88:91], v[60:63], 0
	v_mfma_f32_16x16x32_bf16 v[40:43], v[52:55], v[40:43], v[80:83]
	v_mfma_f32_16x16x32_bf16 v[88:91], v[92:95], v[56:59], v[88:91]
	s_nop 4
	v_cvt_pk_bf16_f32 v80, v100, v101
	v_cvt_pk_bf16_f32 v81, v102, v103
	ds_write_b64 v1, v[80:81]
	v_mfma_f32_16x16x32_bf16 v[36:39], v[48:51], v[36:39], v[40:43]
	v_cvt_pk_bf16_f32 v80, v96, v97
	v_pk_add_f32 v[82:83], v[88:89], v[106:107]
	v_pk_add_f32 v[84:85], v[90:91], v[108:109]
	v_pk_mul_f32 v[82:83], v[0:1], v[82:83] op_sel_hi:[0,1]
	v_pk_mul_f32 v[84:85], v[0:1], v[84:85] op_sel_hi:[0,1]
	s_nop 2
	v_pk_mul_f32 v[38:39], v[46:47], v[38:39]
	v_pk_mul_f32 v[36:37], v[44:45], v[36:37]
	v_cvt_pk_bf16_f32 v81, v98, v99
	v_cvt_pk_bf16_f32 v40, v82, v83
	v_cvt_pk_bf16_f32 v41, v84, v85
	v_cvt_pk_bf16_f32 v36, v36, v37
	v_cvt_pk_bf16_f32 v37, v38, v39
	ds_write2st64_b64 v165, v[40:41], v[80:81] offset0:90 offset1:108
	ds_write_b64 v201, v[36:37] offset:64512
	ds_read_b128 v[40:43], v158
	ds_read_b128 v[36:39], v158 offset:64
	ds_read_b128 v[84:87], v159
	ds_read_b128 v[80:83], v159 offset:64
	ds_read_b64 v[90:91], v160 offset:27648
	s_waitcnt lgkmcnt(4)
	v_mfma_f32_16x16x32_bf16 v[92:95], v[40:43], v[72:75], 0
	s_waitcnt lgkmcnt(0)
	v_lshlrev_b32_e32 v88, 16, v90
	v_and_b32_e32 v89, 0xffff0000, v90
	v_lshlrev_b32_e32 v90, 16, v91
	v_and_b32_e32 v91, 0xffff0000, v91
	v_mfma_f32_16x16x32_bf16 v[76:79], v[32:35], v[76:79], v[92:95]
	s_nop 0
	v_mfma_f32_16x16x32_bf16 v[72:75], v[84:87], v[72:75], v[88:91]
	s_cbranch_vccnz .LBB0_908
	v_mfma_f32_16x16x32_bf16 v[76:79], v[36:39], v[64:67], v[76:79]
	v_mfma_f32_16x16x32_bf16 v[76:79], v[28:31], v[68:71], v[76:79]
	v_mfma_f32_16x16x32_bf16 v[72:75], v[80:83], v[64:67], v[72:75]
.LBB0_908:
	v_mfma_f32_16x16x32_bf16 v[40:43], v[60:63], v[40:43], 0
	s_mul_hi_i32 s8, s90, 0x3e0f83e1
	s_lshr_b32 s9, s8, 31
	s_ashr_i32 s8, s8, 5
	v_mfma_f32_16x16x32_bf16 v[36:39], v[56:59], v[36:39], v[40:43]
	s_add_i32 s8, s8, s9
	v_mov_b32_e32 v1, v0
	s_mulk_i32 s8, 0xdf01
	v_mfma_f32_16x16x32_bf16 v[64:67], v[84:87], v[60:63], 0
	s_add_i32 s8, s26, s8
	s_nop 0
	s_add_i32 s34, s8, 0xffffe110
	v_mfma_f32_16x16x32_bf16 v[32:35], v[52:55], v[32:35], v[36:39]
	s_ashr_i32 s9, s8, 31
	s_cmpk_lt_i32 s8, 0x1ef0
	s_cselect_b32 s8, s8, s34
	v_mfma_f32_16x16x32_bf16 v[64:67], v[80:83], v[56:59], v[64:67]
	v_cvt_pk_bf16_f32 v36, v76, v77
	v_cvt_pk_bf16_f32 v37, v78, v79
	ds_write_b64 v204, v[36:37]
	v_mfma_f32_16x16x32_bf16 v[28:31], v[48:51], v[28:31], v[32:35]
	v_cvt_pk_bf16_f32 v36, v72, v73
	s_nop 2
	v_pk_add_f32 v[38:39], v[64:65], v[110:111]
	v_pk_add_f32 v[40:41], v[66:67], v[112:113]
	v_pk_mul_f32 v[38:39], v[0:1], v[38:39]
	v_pk_mul_f32 v[0:1], v[0:1], v[40:41]
	v_cvt_pk_bf16_f32 v37, v74, v75
	v_cvt_pk_bf16_f32 v32, v38, v39
	v_cvt_pk_bf16_f32 v33, v0, v1
	s_nop 0
	ds_write2st64_b64 v205, v[32:33], v[36:37] offset0:90 offset1:108
	v_pk_mul_f32 v[0:1], v[46:47], v[30:31]
	v_pk_mul_f32 v[28:29], v[44:45], v[28:29]
	s_brev_b32 s34, 50
	v_cvt_pk_bf16_f32 v28, v28, v29
	v_cvt_pk_bf16_f32 v29, v0, v1
	s_cselect_b32 s34, s34, 0x42b80000
	ds_write_b64 v206, v[28:29] offset:64512
	s_cselect_b32 s9, s9, 0
	s_add_u32 s34, s36, s34
	s_waitcnt lgkmcnt(0)
	s_barrier
	s_addc_u32 s35, s37, 0
	s_lshl_b64 s[8:9], s[8:9], 15
	ds_read_b128 v[28:31], v161 offset:46080
	ds_read_b128 v[32:35], v161 offset:55296
	s_add_u32 s8, s34, s8
	s_addc_u32 s9, s35, s9
	ds_read_b128 v[36:39], v207 offset:64512
	ds_read_b128 v[40:43], v162
	v_lshl_add_u64 v[0:1], s[8:9], 0, v[104:105]
	s_movk_i32 s8, 0x2000
	s_waitcnt lgkmcnt(3)
	global_store_dwordx4 v[0:1], v[28:31], off
	s_mov_b32 s84, 0x10000
	s_mov_b32 s85, 0x30000
	v_add_co_u32_e32 v28, vcc, s8, v0
	s_add_i32 s26, s26, 64
	s_nop 0
	v_addc_co_u32_e32 v29, vcc, 0, v1, vcc
	s_waitcnt lgkmcnt(2)
	global_store_dwordx4 v[28:29], v[32:35], off
	v_add_co_u32_e32 v28, vcc, 0x4000, v0
	s_add_i32 s27, s27, -1
	s_nop 0
	v_addc_co_u32_e32 v29, vcc, 0, v1, vcc
	v_add_co_u32_e32 v0, vcc, 0x6000, v0
	s_waitcnt lgkmcnt(1)
	global_store_dwordx4 v[28:29], v[36:39], off
	v_addc_co_u32_e32 v1, vcc, 0, v1, vcc
	s_waitcnt lgkmcnt(0)
	global_store_dwordx4 v[0:1], v[40:43], off
	s_waitcnt lgkmcnt(0)
	s_barrier
	s_andn2_b64 vcc, exec, s[22:23]
	s_cbranch_vccz .LBB0_910
	s_mov_b32 s90, s91
	s_branch .LBB0_867
